# pass2 (s3): gate/OI 8-B loads and Y 8-B stores paired into 16-B accesses via v_permlane16_swap (fq-even/odd lanes)
# speedup vs baseline: 1.0097x; 1.0097x over previous
.LBB0_168:
	s_or_b64 exec, exec, s[4:5]
	v_lshl_add_u64 v[88:89], v[30:31], 0, v[90:91]
	global_load_dwordx4 v[78:81], v[88:89], off
	global_load_dwordx4 v[82:85], v[88:89], off offset:64
	global_load_dwordx4 v[16:19], v[32:33], off offset:192
	global_load_dwordx4 v[20:23], v[32:33], off offset:128
	global_load_dwordx4 v[24:27], v[32:33], off offset:64
	global_load_dwordx4 v[52:55], v[32:33], off
	s_waitcnt lgkmcnt(0)
	v_add_f32_e32 v30, v50, v51
	v_mov_b32_e32 v31, 0x3727c5ac
	v_fmamk_f32 v30, v30, 0x3c800000, v31
	s_mov_b32 s4, 0x800000
	v_cmp_gt_f32_e32 vcc, s4, v30
	v_mul_f32_e32 v31, 0x4b800000, v30
	v_mov_b64_e32 v[32:33], s[68:69]
	s_movk_i32 s8, 0x600
	v_cndmask_b32_e32 v30, v30, v31, vcc
	v_mad_u64_u32 v[32:33], s[4:5], v40, s8, v[32:33]
	v_rsq_f32_e32 v30, v30
	v_mov_b32_e32 v40, v33
	v_mad_u64_u32 v[40:41], s[4:5], v41, s8, v[40:41]
	v_mov_b32_e32 v33, v40
	v_lshl_add_u64 v[32:33], v[32:33], 0, v[44:45]
	v_mul_f32_e32 v31, 0x45800000, v30
	v_lshl_add_u64 v[32:33], v[36:37], 1, v[32:33]
	v_cndmask_b32_e32 v30, v30, v31, vcc
	v_add_u32_e32 v46, s2, v46
	s_movk_i32 s4, 0x1fff
	v_cmp_lt_i32_e32 vcc, s4, v46
	s_movk_i32 s67, 0x600
	v_add_u32_e32 v47, s3, v47
	v_add_u32_e32 v48, s6, v48
	v_add_u32_e32 v49, s7, v49
	s_or_b64 s[84:85], vcc, s[84:85]
	s_waitcnt vmcnt(0)
	v_permlane16_swap_b32_e32 v78, v80
	v_permlane16_swap_b32_e32 v79, v81
	v_permlane16_swap_b32_e32 v82, v84
	v_permlane16_swap_b32_e32 v83, v85
	s_nop 1
	v_lshlrev_b32_e32 v36, 16, v78
	v_mul_f32_e32 v31, 0xbfb8aa3b, v36
	v_exp_f32_e32 v31, v31
	v_and_b32_e32 v37, 0xffff0000, v78
	v_add_f32_e32 v31, 1.0, v31
	v_rcp_f32_e32 v40, v31
	v_pk_mul_f32 v[12:13], v[12:13], v[30:31] op_sel_hi:[1,0]
	v_mul_f32_e32 v31, 0xbfb8aa3b, v37
	v_exp_f32_e32 v31, v31
	v_pk_mul_f32 v[12:13], v[52:53], v[12:13]
	v_add_f32_e32 v31, 1.0, v31
	v_rcp_f32_e32 v41, v31
	s_nop 0
	v_pk_mul_f32 v[36:37], v[40:41], v[36:37]
	s_nop 0
	v_pk_mul_f32 v[12:13], v[36:37], v[12:13]
	s_nop 0
	v_cvt_pk_bf16_f32 v36, v12, v13
	v_lshlrev_b32_e32 v12, 16, v79
	v_mul_f32_e32 v31, 0xbfb8aa3b, v12
	v_exp_f32_e32 v31, v31
	v_and_b32_e32 v13, 0xffff0000, v79
	v_add_f32_e32 v31, 1.0, v31
	v_rcp_f32_e32 v40, v31
	v_pk_mul_f32 v[14:15], v[14:15], v[30:31] op_sel_hi:[1,0]
	v_mul_f32_e32 v31, 0xbfb8aa3b, v13
	v_exp_f32_e32 v31, v31
	v_pk_mul_f32 v[14:15], v[54:55], v[14:15]
	v_add_f32_e32 v31, 1.0, v31
	v_rcp_f32_e32 v41, v31
	v_pk_mul_f32 v[8:9], v[8:9], v[30:31] op_sel_hi:[1,0]
	v_pk_mul_f32 v[10:11], v[10:11], v[30:31] op_sel_hi:[1,0]
	v_pk_mul_f32 v[8:9], v[24:25], v[8:9]
	v_pk_mul_f32 v[12:13], v[40:41], v[12:13]
	v_pk_mul_f32 v[10:11], v[26:27], v[10:11]
	v_pk_mul_f32 v[12:13], v[12:13], v[14:15]
	v_lshlrev_b32_e32 v14, 16, v80
	v_and_b32_e32 v15, 0xffff0000, v80
	v_cvt_pk_bf16_f32 v37, v12, v13
	v_lshl_add_u64 v[12:13], v[28:29], 1, v[32:33]
	v_lshl_add_u64 v[86:87], v[12:13], 0, v[90:91]
	v_mul_f32_e32 v28, 0xbfb8aa3b, v14
	v_mul_f32_e32 v24, 0xbfb8aa3b, v15
	v_exp_f32_e32 v28, v28
	v_exp_f32_e32 v24, v24
	v_pk_mul_f32 v[4:5], v[4:5], v[30:31] op_sel_hi:[1,0]
	v_pk_mul_f32 v[6:7], v[6:7], v[30:31] op_sel_hi:[1,0]
	v_add_f32_e32 v28, 1.0, v28
	v_add_f32_e32 v24, 1.0, v24
	v_rcp_f32_e32 v28, v28
	v_rcp_f32_e32 v29, v24
	v_pk_mul_f32 v[4:5], v[20:21], v[4:5]
	v_pk_mul_f32 v[6:7], v[22:23], v[6:7]
	v_pk_mul_f32 v[0:1], v[0:1], v[30:31] op_sel_hi:[1,0]
	v_pk_mul_f32 v[14:15], v[28:29], v[14:15]
	v_pk_mul_f32 v[0:1], v[16:17], v[0:1]
	v_pk_mul_f32 v[8:9], v[14:15], v[8:9]
	v_lshlrev_b32_e32 v14, 16, v81
	v_cvt_pk_bf16_f32 v8, v8, v9
	v_mul_f32_e32 v9, 0xbfb8aa3b, v14
	v_exp_f32_e32 v9, v9
	v_and_b32_e32 v15, 0xffff0000, v81
	v_pk_mul_f32 v[2:3], v[2:3], v[30:31] op_sel_hi:[1,0]
	v_add_f32_e32 v9, 1.0, v9
	v_rcp_f32_e32 v24, v9
	v_mul_f32_e32 v9, 0xbfb8aa3b, v15
	v_exp_f32_e32 v9, v9
	v_pk_mul_f32 v[2:3], v[18:19], v[2:3]
	v_add_f32_e32 v9, 1.0, v9
	v_rcp_f32_e32 v25, v9
	s_nop 0
	v_pk_mul_f32 v[14:15], v[24:25], v[14:15]
	s_nop 0
	v_pk_mul_f32 v[10:11], v[14:15], v[10:11]
	s_nop 0
	v_cvt_pk_bf16_f32 v9, v10, v11
	v_mov_b32_e32 v70, v36
	v_mov_b32_e32 v71, v37
	v_mov_b32_e32 v72, v8
	v_mov_b32_e32 v73, v9
	s_nop 1
	v_permlane16_swap_b32_e32 v70, v72
	v_permlane16_swap_b32_e32 v71, v73
	s_nop 1
	global_store_dwordx4 v[86:87], v[70:73], off
	v_lshlrev_b32_e32 v8, 16, v82
	v_and_b32_e32 v9, 0xffff0000, v82
	v_mul_f32_e32 v10, 0xbfb8aa3b, v8
	v_mul_f32_e32 v11, 0xbfb8aa3b, v9
	v_exp_f32_e32 v10, v10
	v_exp_f32_e32 v11, v11
	v_add_f32_e32 v10, 1.0, v10
	v_add_f32_e32 v11, 1.0, v11
	v_rcp_f32_e32 v10, v10
	v_rcp_f32_e32 v11, v11
	s_nop 0
	v_pk_mul_f32 v[8:9], v[10:11], v[8:9]
	s_nop 0
	v_pk_mul_f32 v[4:5], v[8:9], v[4:5]
	v_lshlrev_b32_e32 v8, 16, v83
	v_cvt_pk_bf16_f32 v4, v4, v5
	v_mul_f32_e32 v5, 0xbfb8aa3b, v8
	v_exp_f32_e32 v5, v5
	v_and_b32_e32 v9, 0xffff0000, v83
	v_add_f32_e32 v5, 1.0, v5
	v_rcp_f32_e32 v10, v5
	v_mul_f32_e32 v5, 0xbfb8aa3b, v9
	v_exp_f32_e32 v5, v5
	s_nop 0
	v_add_f32_e32 v5, 1.0, v5
	v_rcp_f32_e32 v11, v5
	s_nop 0
	v_pk_mul_f32 v[8:9], v[10:11], v[8:9]
	s_nop 0
	v_pk_mul_f32 v[6:7], v[8:9], v[6:7]
	s_nop 0
	v_cvt_pk_bf16_f32 v5, v6, v7
	v_mov_b32_e32 v74, v4
	v_mov_b32_e32 v75, v5
	v_lshlrev_b32_e32 v4, 16, v84
	v_and_b32_e32 v5, 0xffff0000, v84
	v_mul_f32_e32 v6, 0xbfb8aa3b, v4
	v_mul_f32_e32 v7, 0xbfb8aa3b, v5
	v_exp_f32_e32 v6, v6
	v_exp_f32_e32 v7, v7
	v_add_f32_e32 v6, 1.0, v6
	v_add_f32_e32 v7, 1.0, v7
	v_rcp_f32_e32 v6, v6
	v_rcp_f32_e32 v7, v7
	s_nop 0
	v_pk_mul_f32 v[4:5], v[6:7], v[4:5]
	s_nop 0
	v_pk_mul_f32 v[0:1], v[4:5], v[0:1]
	v_lshlrev_b32_e32 v4, 16, v85
	v_cvt_pk_bf16_f32 v0, v0, v1
	v_mul_f32_e32 v1, 0xbfb8aa3b, v4
	v_exp_f32_e32 v1, v1
	v_and_b32_e32 v5, 0xffff0000, v85
	v_add_f32_e32 v1, 1.0, v1
	v_rcp_f32_e32 v6, v1
	v_mul_f32_e32 v1, 0xbfb8aa3b, v5
	v_exp_f32_e32 v1, v1
	s_nop 0
	v_add_f32_e32 v1, 1.0, v1
	v_rcp_f32_e32 v7, v1
	s_nop 0
	v_pk_mul_f32 v[4:5], v[6:7], v[4:5]
	s_nop 0
	v_pk_mul_f32 v[2:3], v[4:5], v[2:3]
	s_nop 0
	v_cvt_pk_bf16_f32 v1, v2, v3
	v_mov_b32_e32 v76, v0
	v_mov_b32_e32 v77, v1
	s_nop 1
	v_permlane16_swap_b32_e32 v74, v76
	v_permlane16_swap_b32_e32 v75, v77
	s_nop 1
	global_store_dwordx4 v[86:87], v[74:77], off offset:64
	s_andn2_b64 exec, exec, s[84:85]
	s_cbranch_execz .LBB0_173
.LBB0_169:
	s_movk_i32 s4, 0xfff
	v_cmp_lt_i32_e32 vcc, s4, v46
	s_and_saveexec_b64 s[4:5], vcc
	s_xor_b64 s[4:5], exec, s[4:5]
	s_cbranch_execz .LBB0_171
	v_mov_b32_e32 v1, v206
	v_add_u32_e32 v0, 0xfffff000, v46
	v_lshrrev_b32_e32 v2, 9, v0
	v_and_b32_e32 v18, 15, v1
	v_bfe_u32 v19, v1, 4, 2
	v_and_b32_e32 v90, 1, v19
	v_mul_u32_u24_e32 v90, 24, v90
	v_mov_b32_e32 v91, 0
	v_bfe_u32 v3, v0, 9, 2
	v_and_b32_e32 v0, 0x2000, v49
	v_and_b32_e32 v1, 0x1ff0, v48
	v_or3_b32 v176, v0, v1, v18
	v_lshlrev_b32_e32 v0, 8, v3
	v_mov_b32_e32 v1, v177
	v_lshl_add_u64 v[4:5], s[38:39], 0, v[0:1]
	v_and_b32_e32 v0, 0x3f800, v47
	v_lshlrev_b32_e32 v0, 1, v0
	v_lshl_or_b32 v0, v2, 19, v0
	v_lshlrev_b32_e32 v2, 8, v176
	v_lshl_add_u64 v[6:7], s[60:61], 0, v[0:1]
	v_lshlrev_b32_e32 v0, 10, v176
	v_sub_co_u32_e32 v2, vcc, 0, v2
	v_lshlrev_b32_e32 v36, 6, v3
	v_lshl_add_u64 v[0:1], s[68:69], 0, v[0:1]
	v_lshlrev_b32_e32 v8, 7, v3
	v_subb_co_u32_e64 v3, s[8:9], 0, 0, vcc
	v_mov_b32_e32 v37, v177
	v_mov_b32_e32 v9, v177
	v_lshl_add_u64 v[12:13], v[0:1], 0, v[2:3]
	v_lshl_add_u64 v[10:11], v[0:1], 0, v[8:9]
	v_lshl_add_u64 v[0:1], v[12:13], 0, v[36:37]
	v_lshlrev_b32_e32 v16, 4, v19
	v_mov_b32_e32 v17, v177
	v_lshlrev_b32_e32 v14, 3, v19
	v_mov_b32_e32 v15, v177
	v_lshl_add_u64 v[0:1], v[0:1], 0, v[16:17]
	s_mov_b32 s8, 0xece4000
	v_add_co_u32_e32 v0, vcc, s8, v0
	v_lshl_add_u64 v[10:11], v[10:11], 0, v[14:15]
	s_mov_b64 s[8:9], 0xdce4200
	v_lshl_add_u64 v[20:21], v[10:11], 0, s[8:9]
	v_lshl_add_u64 v[92:93], v[20:21], 0, v[90:91]
	s_movk_i32 s8, 0x1100
	v_mad_u64_u32 v[12:13], s[8:9], v176, s8, v[12:13]
	v_lshl_add_u64 v[8:9], v[12:13], 0, v[8:9]
	v_lshl_add_u64 v[8:9], v[8:9], 0, v[14:15]
	s_mov_b64 s[8:9], 0x3e81200
	v_addc_co_u32_e32 v1, vcc, 0, v1, vcc
	v_lshl_add_u64 v[30:31], v[8:9], 0, s[8:9]
	s_mov_b32 s8, 0xdce4000
	v_lshl_add_u64 v[32:33], v[4:5], 0, v[16:17]
	v_lshl_add_u64 v[4:5], v[6:7], 0, v[16:17]
	v_add_co_u32_e32 v6, vcc, s8, v10
	global_load_dwordx4 v[0:3], v[0:1], off offset:512
	s_nop 0
	v_addc_co_u32_e32 v7, vcc, 0, v11, vcc
	global_load_dwordx4 v[62:65], v[92:93], off
	global_load_dwordx4 v[66:69], v[92:93], off offset:64
	v_lshlrev_b32_e32 v6, 6, v18
	v_mov_b32_e32 v7, v177
	v_lshl_add_u64 v[12:13], v[4:5], 0, v[6:7]
	v_lshlrev_b32_e32 v28, 2, v19
	global_load_dwordx4 v[4:7], v[12:13], off
	global_load_dwordx4 v[8:11], v[12:13], off offset:1024
	global_load_dwordx4 v[16:19], v[12:13], off offset:2048
	s_nop 0
	global_load_dwordx4 v[20:23], v[12:13], off offset:3072
	v_mov_b32_e32 v29, v177
	v_mov_b64_e32 v[40:41], v[176:177]
	s_waitcnt vmcnt(0)
	v_permlane16_swap_b32_e32 v62, v64
	v_permlane16_swap_b32_e32 v63, v65
	v_permlane16_swap_b32_e32 v66, v68
	v_permlane16_swap_b32_e32 v67, v69
	s_nop 1
	v_lshlrev_b32_e32 v12, 16, v62
	v_and_b32_e32 v13, 0xffff0000, v62
	v_lshlrev_b32_e32 v14, 16, v63
	v_and_b32_e32 v15, 0xffff0000, v63
	s_nop 1
	v_mfma_f32_16x16x32_bf16 v[12:15], v[4:7], v[0:3], v[12:15]
	v_lshlrev_b32_e32 v4, 16, v64
	v_and_b32_e32 v5, 0xffff0000, v64
	v_lshlrev_b32_e32 v6, 16, v65
	v_and_b32_e32 v7, 0xffff0000, v65
	s_nop 1
	v_mfma_f32_16x16x32_bf16 v[8:11], v[8:11], v[0:3], v[4:7]
	s_nop 2
	v_lshlrev_b32_e32 v4, 16, v66
	v_and_b32_e32 v5, 0xffff0000, v66
	v_lshlrev_b32_e32 v6, 16, v67
	v_and_b32_e32 v7, 0xffff0000, v67
	s_nop 1
	v_mfma_f32_16x16x32_bf16 v[4:7], v[16:19], v[0:3], v[4:7]
	v_lshlrev_b32_e32 v16, 16, v68
	v_and_b32_e32 v17, 0xffff0000, v68
	v_lshlrev_b32_e32 v18, 16, v69
	v_and_b32_e32 v19, 0xffff0000, v69
	s_nop 1
	v_mfma_f32_16x16x32_bf16 v[0:3], v[20:23], v[0:3], v[16:19]
	v_mul_f32_e32 v20, v13, v13
	v_fmac_f32_e32 v20, v12, v12
	v_fmac_f32_e32 v20, v14, v14
	v_fmac_f32_e32 v20, v15, v15
	v_pk_mul_f32 v[18:19], v[8:9], v[8:9]
	v_pk_mul_f32 v[16:17], v[10:11], v[10:11]
	v_add_f32_e32 v18, v18, v20
	v_add_f32_e32 v18, v19, v18
	v_add_f32_e32 v16, v16, v18
	v_add_f32_e32 v20, v17, v16
	v_pk_mul_f32 v[18:19], v[4:5], v[4:5]
	v_pk_mul_f32 v[16:17], v[6:7], v[6:7]
	v_add_f32_e32 v18, v18, v20
	v_add_f32_e32 v18, v19, v18
	v_add_f32_e32 v16, v16, v18
	v_add_f32_e32 v20, v17, v16
	v_pk_mul_f32 v[18:19], v[0:1], v[0:1]
	v_pk_mul_f32 v[16:17], v[2:3], v[2:3]
	v_add_f32_e32 v18, v18, v20
	v_add_f32_e32 v18, v19, v18
	v_add_f32_e32 v16, v16, v18
	v_and_b32_e32 v18, 64, v210
	v_add_f32_e32 v16, v17, v16
	v_xor_b32_e32 v17, 16, v210
	v_add_u32_e32 v18, 64, v18
	v_cmp_lt_i32_e32 vcc, v17, v18
	s_nop 1
	v_cndmask_b32_e32 v17, v210, v17, vcc
	v_lshlrev_b32_e32 v17, 2, v17
	ds_bpermute_b32 v17, v17, v16
	s_waitcnt lgkmcnt(0)
	v_add_f32_e32 v50, v16, v17
	v_xor_b32_e32 v16, 32, v210
	v_cmp_lt_i32_e32 vcc, v16, v18
	s_nop 1
	v_cndmask_b32_e32 v16, v210, v16, vcc
	v_lshlrev_b32_e32 v16, 2, v16
	ds_bpermute_b32 v51, v16, v50
.LBB0_171:
	s_or_saveexec_b64 s[4:5], s[4:5]
	v_mov_b64_e32 v[44:45], 0x9e80400
	s_xor_b64 exec, exec, s[4:5]
	s_cbranch_execz .LBB0_168
	v_mov_b32_e32 v0, v206
	v_and_b32_e32 v2, 0x1ff, v46
	v_and_b32_e32 v20, 15, v0
	v_bfe_u32 v21, v0, 4, 2
	v_and_b32_e32 v90, 1, v21
	v_mul_u32_u24_e32 v90, 24, v90
	v_mov_b32_e32 v91, 0
	v_ashrrev_i32_e32 v0, 11, v46
	v_ashrrev_i32_e32 v1, 31, v0
	v_ashrrev_i32_e32 v3, 9, v46
	v_lshlrev_b64 v[40:41], 13, v[0:1]
	v_lshlrev_b32_e32 v0, 4, v2
	v_or3_b32 v40, v40, v0, v20
	v_lshlrev_b32_e32 v0, 6, v3
	v_and_b32_e32 v176, 0xc0, v0
	v_bfe_u32 v6, v46, 2, 7
	v_lshlrev_b32_e32 v0, 2, v176
	v_mov_b32_e32 v1, v177
	v_lshl_add_u64 v[4:5], s[40:41], 0, v[0:1]
	v_lshl_or_b32 v0, v3, 7, v6
	v_ashrrev_i32_e32 v1, 31, v0
	v_lshlrev_b64 v[6:7], 13, v[0:1]
	v_lshlrev_b64 v[0:1], 10, v[40:41]
	v_lshl_add_u64 v[8:9], s[62:63], 0, v[0:1]
	v_mov_b64_e32 v[0:1], s[64:65]
	s_movk_i32 s10, 0x300
	v_mad_u64_u32 v[0:1], s[8:9], v40, s10, v[0:1]
	v_mad_i32_i24 v1, v41, s10, v1
	v_lshlrev_b32_e32 v10, 1, v176
	v_mov_b32_e32 v11, v177
	v_lshl_add_u64 v[0:1], v[0:1], 0, v[10:11]
	v_lshlrev_b32_e32 v12, 3, v21
	v_mov_b32_e32 v13, v177
	v_lshlrev_b32_e32 v14, 4, v21
	v_mov_b32_e32 v15, v177
	v_lshl_add_u64 v[8:9], v[8:9], 0, v[10:11]
	v_lshl_add_u64 v[16:17], v[0:1], 0, v[14:15]
	v_lshl_add_u64 v[6:7], s[74:75], 0, v[6:7]
	v_lshl_add_u64 v[38:39], v[8:9], 0, v[12:13]
	v_lshl_add_u64 v[92:93], v[38:39], 0, v[90:91]
	global_load_dwordx4 v[0:3], v[16:17], off
	s_nop 0
	global_load_dwordx4 v[16:19], v[16:17], off offset:64
	v_lshl_add_u64 v[32:33], v[4:5], 0, v[14:15]
	v_lshl_add_u64 v[4:5], v[6:7], 0, v[14:15]
	global_load_dwordx4 v[62:65], v[92:93], off
	v_mov_b64_e32 v[8:9], s[68:69]
	v_mad_u64_u32 v[8:9], s[8:9], v40, s13, v[8:9]
	v_mad_i32_i24 v9, v41, s13, v9
	v_lshl_add_u64 v[8:9], v[8:9], 0, v[10:11]
	v_lshlrev_b32_e32 v6, 7, v20
	v_mov_b32_e32 v7, v177
	v_lshl_add_u64 v[8:9], v[8:9], 0, v[12:13]
	s_mov_b64 s[8:9], 0x3e80c00
	v_lshl_add_u64 v[12:13], v[4:5], 0, v[6:7]
	v_lshlrev_b32_e32 v28, 2, v21
	v_lshl_add_u64 v[30:31], v[8:9], 0, s[8:9]
	global_load_dwordx4 v[4:7], v[12:13], off
	global_load_dwordx4 v[8:11], v[12:13], off offset:64
	global_load_dwordx4 v[20:23], v[12:13], off offset:2048
	global_load_dwordx4 v[24:27], v[12:13], off offset:2112
	global_load_dwordx4 v[66:69], v[92:93], off offset:64
	s_movk_i32 s8, 0x1000
	v_add_co_u32_e32 v12, vcc, s8, v12
	v_mov_b32_e32 v29, v177
	s_nop 0
	v_addc_co_u32_e32 v13, vcc, 0, v13, vcc
	global_load_dwordx4 v[34:37], v[12:13], off
	global_load_dwordx4 v[42:45], v[12:13], off offset:64
	s_nop 0
	s_waitcnt lgkmcnt(0)
	global_load_dwordx4 v[50:53], v[12:13], off offset:2048
	global_load_dwordx4 v[54:57], v[12:13], off offset:2112
	s_waitcnt vmcnt(0)
	v_permlane16_swap_b32_e32 v62, v64
	v_permlane16_swap_b32_e32 v63, v65
	v_permlane16_swap_b32_e32 v66, v68
	v_permlane16_swap_b32_e32 v67, v69
	s_nop 1
	v_lshlrev_b32_e32 v12, 16, v62
	v_and_b32_e32 v13, 0xffff0000, v62
	v_lshlrev_b32_e32 v14, 16, v63
	v_and_b32_e32 v15, 0xffff0000, v63
	s_nop 1
	v_mfma_f32_16x16x32_bf16 v[4:7], v[4:7], v[0:3], v[12:15]
	v_mfma_f32_16x16x32_bf16 v[12:15], v[8:11], v[16:19], v[4:7]
	s_nop 6
	v_lshlrev_b32_e32 v4, 16, v64
	v_and_b32_e32 v5, 0xffff0000, v64
	v_lshlrev_b32_e32 v6, 16, v65
	v_and_b32_e32 v7, 0xffff0000, v65
	s_nop 1
	v_mfma_f32_16x16x32_bf16 v[4:7], v[20:23], v[0:3], v[4:7]
	v_lshlrev_b32_e32 v20, 16, v68
	v_and_b32_e32 v21, 0xffff0000, v68
	v_lshlrev_b32_e32 v22, 16, v69
	v_mfma_f32_16x16x32_bf16 v[8:11], v[24:27], v[16:19], v[4:7]
	v_and_b32_e32 v23, 0xffff0000, v69
	s_nop 2
	v_lshlrev_b32_e32 v4, 16, v66
	v_and_b32_e32 v5, 0xffff0000, v66
	v_lshlrev_b32_e32 v6, 16, v67
	v_and_b32_e32 v7, 0xffff0000, v67
	s_nop 1
	v_mfma_f32_16x16x32_bf16 v[4:7], v[34:37], v[0:3], v[4:7]
	v_mov_b64_e32 v[36:37], v[176:177]
	v_mfma_f32_16x16x32_bf16 v[0:3], v[50:53], v[0:3], v[20:23]
	s_nop 2
	v_mul_f32_e32 v20, v13, v13
	v_fmac_f32_e32 v20, v12, v12
	v_fmac_f32_e32 v20, v14, v14
	v_mfma_f32_16x16x32_bf16 v[4:7], v[42:45], v[16:19], v[4:7]
	v_fmac_f32_e32 v20, v15, v15
	v_mov_b64_e32 v[44:45], 0x9e80200
	v_mfma_f32_16x16x32_bf16 v[0:3], v[54:57], v[16:19], v[0:3]
	v_mul_f32_e64 v18, v8, v8
	v_mul_f32_e64 v19, v9, v9
	v_pk_mul_f32 v[16:17], v[10:11], v[10:11]
	v_add_f32_e32 v18, v18, v20
	v_add_f32_e32 v18, v19, v18
	v_add_f32_e32 v16, v16, v18
	v_add_f32_e32 v20, v17, v16
	v_pk_mul_f32 v[18:19], v[4:5], v[4:5]
	v_pk_mul_f32 v[16:17], v[6:7], v[6:7]
	v_add_f32_e32 v18, v18, v20
	v_add_f32_e32 v18, v19, v18
	v_add_f32_e32 v16, v16, v18
	v_add_f32_e32 v20, v17, v16
	v_pk_mul_f32 v[18:19], v[0:1], v[0:1]
	v_pk_mul_f32 v[16:17], v[2:3], v[2:3]
	v_add_f32_e32 v18, v18, v20
	v_add_f32_e32 v18, v19, v18
	v_add_f32_e32 v16, v16, v18
	v_and_b32_e32 v18, 64, v210
	v_add_f32_e32 v16, v17, v16
	v_xor_b32_e32 v17, 16, v210
	v_add_u32_e32 v18, 64, v18
	v_cmp_lt_i32_e32 vcc, v17, v18
	s_nop 1
	v_cndmask_b32_e32 v17, v210, v17, vcc
	v_lshlrev_b32_e32 v17, 2, v17
	ds_bpermute_b32 v17, v17, v16
	s_waitcnt lgkmcnt(0)
	v_add_f32_e32 v50, v16, v17
	v_xor_b32_e32 v16, 32, v210
	v_cmp_lt_i32_e32 vcc, v16, v18
	s_nop 1
	v_cndmask_b32_e32 v16, v210, v16, vcc
	v_lshlrev_b32_e32 v16, 2, v16
	ds_bpermute_b32 v51, v16, v50
	s_branch .LBB0_168
